# v45 + static s_setprio 1 for waves 4-7 (prio 0 for waves 0-3) in the mixer loops
# baseline (speedup 1.0000x reference)
; #define LAS __attribute__((address_space(3)))
; __device__ __forceinline__ void attn_load(AttnKV& R, bf16x8 (&q)[8], int au, const bf16_t* Qg, const bf16_t* Kg, const bf16_t* Vg, int tid) {
;     const int wid = tid >> 6, lane = tid & 63, fr = lane & 15, fq = lane >> 4;
;     const int b = au >> 9, blk = (au >> 2) & 127, kvh = au & 3;
;     const int tok0 = b * SEQ + blk * 128;
; #pragma unroll
;     for (int it = 0; it < 4; ++it) { const int c = it * NTHREADS + tid, key = c >> 3, dc = c & 7;
;         u32x4 v = (u32x4){0u, 0u, 0u, 0u};
;         if (blk > 0 || key >= 128) v = *(const u32x4*)(Kg + (size_t)(tok0 - 128 + key) * 256 + kvh * 64 + dc * 8);
;         R.k[it] = v; }
; __device__ __forceinline__ void mixer_phase(LAS unsigned char* lds, unsigned char* ws, const float* sinks, const float* bsp, int tid) {
;     const int G = gridDim.x;
;     const bf16_t* Qg = (const bf16_t*)(ws + WS_Q); const bf16_t* Kg = (const bf16_t*)(ws + WS_K); const bf16_t* Vg = (const bf16_t*)(ws + WS_V);
;     const bf16_t* GU = (const bf16_t*)(ws + WS_GU); const bf16_t* GV = (const bf16_t*)(ws + WS_GV); const bf16_t* WSB = (const bf16_t*)(ws + WS_WSB);
;     bf16_t* AO = (bf16_t*)(ws + WS_AO); float* partA = (float*)(ws + WS_PARTA); float* partB = (float*)(ws + WS_PARTB); const float* partG = (const float*)(ws + WS_PARTG);
;     {
;         constexpr int NA = BATCH * 128 * 4;
;         int au = blockIdx.x, par = 0; AttnKV R; bf16x8 q[8], qn[8];
;         if (au < NA) { attn_load(R, q, au, Qg, Kg, Vg, tid); attn_store_lds(R, lds, tid); }
.LBB0_539:
	s_cmp_lt_i32 s30, 6
	s_cselect_b64 s[6:7], -1, 0
	s_add_u32 s0, s28, 0x20a00000
	s_addc_u32 s1, s29, 0
	s_add_u32 s24, s28, 0xa200000
	s_addc_u32 s25, s29, 0
	s_waitcnt lgkmcnt(0)
	s_add_u32 s36, s28, 0xa400000
	s_addc_u32 s37, s29, 0
	s_and_b64 s[38:39], s[6:7], s[4:5]
	s_andn2_b64 vcc, exec, s[38:39]
	s_cbranch_vccnz .LBB0_580
	s_setprio 0
	v_readfirstlane_b32 s6, v212
	s_nop 0
	s_cmpk_lt_u32 s6, 0x100
	s_cbranch_scc1 .Lmx_prio_done
	s_setprio 1
.Lmx_prio_done:
	s_add_u32 s6, s28, 0x16a00000
	s_addc_u32 s7, s29, 0
	s_add_u32 s4, s28, 0x17a00000
	s_addc_u32 s5, s29, 0
	s_cmpk_lt_i32 s2, 0x400
	s_cselect_b64 s[8:9], -1, 0
	s_cmpk_gt_i32 s2, 0x3ff
	v_lshlrev_b32_e32 v108, 3, v212
	s_cbranch_scc1 .LBB0_543
	s_bfe_u32 s34, s2, 0x70002
	s_lshl_b32 s10, s2, 5
	s_and_b32 s10, s10, 0xffffc000
	s_lshl_b32 s11, s34, 7
	s_and_b32 s3, s2, 3
	s_or_b32 s18, s11, s10
	s_cmp_lg_u32 s34, 0
	s_cselect_b64 s[10:11], -1, 0
	s_add_i32 s19, s18, 0xffffff80
	s_lshl_b32 s33, s3, 6
	s_lshl_b32 s12, s3, 7
	s_add_u32 s12, s6, s12
	s_waitcnt vmcnt(0)
	v_and_b32_e32 v36, 56, v108
	s_addc_u32 s13, s7, 0
	v_mov_b32_e32 v17, 0
	v_lshlrev_b32_e32 v16, 1, v36
	s_cmp_eq_u32 s34, 0
	v_lshl_add_u64 v[8:9], s[12:13], 0, v[16:17]
	s_cbranch_scc1 .LBB0_544
	v_lshrrev_b32_e32 v0, 3, v212
	v_or_b32_e32 v0, s19, v0
	v_ashrrev_i32_e32 v1, 31, v0
	v_lshlrev_b64 v[0:1], 9, v[0:1]
	v_lshl_add_u64 v[0:1], v[8:9], 0, v[0:1]
	global_load_dwordx4 v[0:3], v[0:1], off
	s_branch .LBB0_545

; __device__ __forceinline__ unsigned xb_ld(unsigned* p)              { return __hip_atomic_load(p, __ATOMIC_RELAXED, __HIP_MEMORY_SCOPE_AGENT); }
; __device__ __forceinline__ void xcd_barrier_complete(unsigned* bar, unsigned x, unsigned& nloc, unsigned& nx) {
;     const unsigned G = gridDim.x * gridDim.y * gridDim.z;
;     unsigned sum, cnt, mine, sp = 0u;
;     for (;;) {
;         sum = 0u; cnt = 0u; mine = 0u;
; #pragma unroll
;         for (unsigned j = 0; j < 16; ++j) { const unsigned c = xb_ld(&bar[XB_XCNT(j)]); sum += c; cnt += (c > 0u) ? 1u : 0u; mine = (j == x) ? c : mine; }
; __device__ __forceinline__ void xcd_barrier(const XcdBarrier& b) {
;     asm volatile("s_waitcnt vmcnt(0)" ::: "memory");
;     __syncthreads();
;     if (threadIdx.x == 0) {
;         unsigned* bar = b.bar;
;         __builtin_amdgcn_s_waitcnt(0);
;         unsigned nloc = b.st[0], nx = b.st[1];
;         if (nloc == 0u) { xcd_barrier_complete(bar, b.x, nloc, nx); b.st[0] = nloc; b.st[1] = nx; }
.LBB0_580:
	s_setprio 0
	s_cmp_gt_u32 s31, 6
	s_cselect_b64 s[4:5], -1, 0
	s_and_b64 s[4:5], s[38:39], s[4:5]
	s_andn2_b64 vcc, exec, s[4:5]
	s_cbranch_vccnz .LBB0_634
	s_waitcnt vmcnt(0)
	s_waitcnt vmcnt(0)
	s_barrier
	s_and_saveexec_b64 s[4:5], s[84:85]
	s_cbranch_execz .LBB0_633
	s_add_i32 s3, 0, 0x23ff0
	v_mov_b32_e32 v0, s3
	s_waitcnt vmcnt(0) expcnt(0) lgkmcnt(0)
	ds_read_b32 v2, v0
	s_add_i32 s3, 0, 0x23ff4
	v_mov_b32_e32 v0, s3
	ds_read_b32 v0, v0
	s_waitcnt lgkmcnt(1)
	v_cmp_ne_u32_e32 vcc, 0, v2
	s_cbranch_vccnz .LBB0_597
	s_add_u32 s6, s28, 0x9dc0200
	s_addc_u32 s7, s29, 0
	s_add_u32 s8, s28, 0x9dc0400
	s_addc_u32 s9, s29, 0
	s_add_u32 s10, s28, 0x9dc0500
	s_addc_u32 s11, s29, 0
	s_add_u32 s12, s28, 0x9dc0600
	s_addc_u32 s13, s29, 0
	s_add_u32 s38, s28, 0x9dc0700
	s_addc_u32 s39, s29, 0
	s_add_u32 s40, s28, 0x9dc0800
	s_addc_u32 s41, s29, 0
	s_add_u32 s42, s28, 0x9dc0900
	s_addc_u32 s43, s29, 0
	s_add_u32 s44, s28, 0x9dc0a00
	s_addc_u32 s45, s29, 0
	s_add_u32 s46, s28, 0x9dc0b00
	s_addc_u32 s47, s29, 0
	s_add_u32 s48, s28, 0x9dc0c00
	s_addc_u32 s49, s29, 0
	s_add_u32 s50, s28, 0x9dc0d00
	s_addc_u32 s51, s29, 0
	s_add_u32 s52, s28, 0x9dc0e00
	s_addc_u32 s53, s29, 0
	s_add_u32 s54, s28, 0x9dc0f00
	s_addc_u32 s55, s29, 0
	s_add_u32 s56, s28, 0x9dc1000
	s_addc_u32 s57, s29, 0
	s_add_u32 s58, s28, 0x9dc1100
	s_addc_u32 s59, s29, 0
	s_add_u32 s60, s28, 0x9dc1200
	s_addc_u32 s61, s29, 0
	s_mul_i32 s3, s23, s83
	s_add_u32 s62, s28, 0x9dc1300
	s_mul_i32 s3, s3, s22
	s_addc_u32 s63, s29, 0
	s_mov_b32 s18, 1
	v_mov_b32_e32 v16, 0
	s_branch .LBB0_585
